# G2(seg0)->G1(seg1) grid barrier replaced by a per-XCD 32-block counter rendezvous (only a same-XCD write-after-read hazard on P); rendezvous poll caps raised
# speedup vs baseline: 1.0108x; 1.0050x over previous
; DI unsigned xb_ld(unsigned* p)              { return __hip_atomic_load(p, __ATOMIC_RELAXED, __HIP_MEMORY_SCOPE_AGENT); }
; __global__ void __launch_bounds__(NT, 2) fwd_megakernel(Params p) {
;     ...
;     int vb = bid, vc = bid;
;     if (G == 256 && lo == 0 && hi > 1) {
;         bool ok = true;
;         for (int j = 0; j < 8; ++j) ok = ok && (xb_ld(&slotw[64 * j]) == 32u);
;         if (ok) { const int xc = (int)xst[2], sl = (int)xst[3]; vb = xc * 32 + sl; vc = sl * 8 + xc; }
;     }
;     vb = __builtin_amdgcn_readfirstlane(vb); vc = __builtin_amdgcn_readfirstlane(vc);
.LBB0_108:
	v_writelane_b32 v250, 0, 60
	v_writelane_b32 v250, 4, 61
	v_writelane_b32 v250, 32, 62
	s_cmp_gt_i32 s33, 1
	s_cselect_b64 s[0:1], -1, 0
	s_and_b64 s[0:1], s[6:7], s[0:1]
	s_andn2_b64 vcc, exec, s[0:1]
	v_mov_b32_e32 v2, s53
	v_mov_b32_e32 v1, s53
	s_cbranch_vccnz .LBB0_118
	v_mov_b32_e32 v1, 0
	global_load_dword v1, v1, s[2:3] sc1
	v_mov_b32_e32 v2, s53
	s_waitcnt vmcnt(0)
	v_cmp_ne_u32_e32 vcc, 32, v1
	v_mov_b32_e32 v1, s53
	s_cbranch_vccnz .LBB0_118
	v_mov_b32_e32 v3, 0x3000
	global_load_dword v1, v3, s[92:93] offset:1792 sc1
	v_mov_b32_e32 v2, s53
	s_waitcnt vmcnt(0)
	v_cmp_ne_u32_e32 vcc, 32, v1
	v_mov_b32_e32 v1, s53
	s_cbranch_vccnz .LBB0_118
	global_load_dword v1, v3, s[92:93] offset:2048 sc1
	v_mov_b32_e32 v2, s53
	s_waitcnt vmcnt(0)
	v_cmp_ne_u32_e32 vcc, 32, v1
	v_mov_b32_e32 v1, s53
	s_cbranch_vccnz .LBB0_118
	v_mov_b32_e32 v3, 0x3000
	global_load_dword v1, v3, s[92:93] offset:2304 sc1
	v_mov_b32_e32 v2, s53
	s_waitcnt vmcnt(0)
	v_cmp_ne_u32_e32 vcc, 32, v1
	v_mov_b32_e32 v1, s53
	s_cbranch_vccnz .LBB0_118
	global_load_dword v1, v3, s[92:93] offset:2560 sc1
	v_mov_b32_e32 v2, s53
	s_waitcnt vmcnt(0)
	v_cmp_ne_u32_e32 vcc, 32, v1
	v_mov_b32_e32 v1, s53
	s_cbranch_vccnz .LBB0_118
	v_mov_b32_e32 v3, 0x3000
	global_load_dword v1, v3, s[92:93] offset:2816 sc1
	v_mov_b32_e32 v2, s53
	s_waitcnt vmcnt(0)
	v_cmp_ne_u32_e32 vcc, 32, v1
	v_mov_b32_e32 v1, s53
	s_cbranch_vccnz .LBB0_118
	global_load_dword v1, v3, s[92:93] offset:3072 sc1
	v_mov_b32_e32 v2, s53
	s_waitcnt vmcnt(0)
	v_cmp_ne_u32_e32 vcc, 32, v1
	v_mov_b32_e32 v1, s53
	s_cbranch_vccnz .LBB0_118
	v_mov_b32_e32 v1, 0x3000
	global_load_dword v1, v1, s[92:93] offset:3328 sc1
	v_mov_b32_e32 v2, s53
	s_waitcnt vmcnt(0)
	v_cmp_ne_u32_e32 vcc, 32, v1
	v_mov_b32_e32 v1, s53
	s_cbranch_vccnz .LBB0_118
	v_writelane_b32 v250, 1, 60
	s_add_i32 s0, 0, 0x23ff8
	v_mov_b32_e32 v1, s0
	s_add_i32 s0, 0, 0x23ffc
	ds_read_b32 v2, v1
	v_mov_b32_e32 v1, s0
	ds_read_b32 v1, v1
	s_waitcnt lgkmcnt(0)
	v_lshlrev_b32_e32 v3, 5, v2
	v_lshlrev_b32_e32 v4, 3, v1
	v_add_u32_e32 v1, v3, v1
	v_add_u32_e32 v2, v4, v2

; DI unsigned xb_ld(unsigned* p)              { return __hip_atomic_load(p, __ATOMIC_RELAXED, __HIP_MEMORY_SCOPE_AGENT); }
; DI unsigned xb_add(unsigned* p, unsigned v) { return __hip_atomic_fetch_add(p, v, __ATOMIC_RELAXED, __HIP_MEMORY_SCOPE_AGENT); }
; #define XB_SPIN(cond, bar) do { unsigned _sp = 0; while (cond) { __builtin_amdgcn_s_sleep(1); \
;     if ((++_sp & 255u) == 0u) { if (xb_ld(&(bar)[XB_TMO])) break; if (_sp > XB_SPIN_CAP) { atomicAdd(&(bar)[XB_TMO], 1u); break; } } } } while (0)
; DI void xcd_barrier(const XcdBarrier& b) {
;     asm volatile("s_waitcnt vmcnt(0)" ::: "memory");
;     __syncthreads();
;     if (threadIdx.x == 0) {
;         unsigned* bar = b.bar;
;         __builtin_amdgcn_s_waitcnt(0);
;         unsigned nloc = b.st[0], nx = b.st[1];
;         if (nloc == 0u) { xcd_barrier_complete(bar, b.x, nloc, nx); b.st[0] = nloc; b.st[1] = nx; }
;         const unsigned old = xb_add(&bar[XB_XSUB(b.x)], 1u);
;         const unsigned gen = old / nloc;
;         if (old + 1u == (gen + 1u) * nloc) {
;             __builtin_amdgcn_fence(__ATOMIC_RELEASE, "agent");
;             asm volatile("s_waitcnt vmcnt(0)" ::: "memory");
;             const unsigned og = xb_add(&bar[XB_TOP], 1u);
;             const unsigned tg = og / nx;
;             if (og + 1u == (tg + 1u) * nx) xb_add(&bar[XB_TOPGEN], 1u);
;             else XB_SPIN(xb_ld(&bar[XB_TOPGEN]) == tg, bar);
;             __builtin_amdgcn_fence(__ATOMIC_ACQUIRE, "agent");
;             xb_add(&bar[XB_XGEN(b.x)], 1u);
;             asm volatile("s_waitcnt vmcnt(0)" ::: "memory");
;         } else {
;             XB_SPIN(xb_ld(&bar[XB_TOPGEN]) == gen, bar);
;             __builtin_amdgcn_fence(__ATOMIC_ACQUIRE, "agent");
;             asm volatile("s_waitcnt vmcnt(0)" ::: "memory");
;         }
;     }
;     __syncthreads();
.Lppg2_poll:
	global_load_dword v148, v146, s[40:41] sc1
	s_waitcnt vmcnt(0)
	v_readfirstlane_b32 s6, v148
	s_cmp_ge_u32 s6, s42
	s_cbranch_scc1 .Lppg2_done
	s_add_i32 s43, s43, 1
	s_sleep 1
	s_cmp_lt_u32 s43, 0x400000
	s_cbranch_scc1 .Lppg2_poll

; #define RUNR(rep, ...) do { if (ph >= lo && ph < hi) { for (int r_ = 0; r_ < (rep); ++r_) { __VA_ARGS__; if (r_ + 1 < (rep) || ph + 1 < hi) GSYNC(); } } ++ph; } while (0)
; __global__ void __launch_bounds__(NT, 2) fwd_megakernel(Params p) {
;     ...
;             RUNR(REP_G1, { phase_tables(p, l, seg, G, bid); pg8::Gemm g{(const bf16_t*)(p.ws + WS_H), (const bf16_t*)(p.ws + WS_WIN) + (size_t)l * NPC * D, D, D, MSEG / 256, NPC / 256, seg, 0};
;                   pg8::EpiP E{(bf16_t*)(p.ws + WS_P), p.pos, (const float*)(p.ws + WS_INVF), seg};
;                   pg8::gemm_phase(lds, g, G, vc, E); });
.LBB0_851:
	v_readlane_b32 s0, v250, 58
	s_add_i32 s71, s0, 7
	s_cmp_ge_i32 s71, s33
	s_cbranch_scc1 .LBB0_216
	v_readlane_b32 s8, v252, 20
	v_readlane_b32 s9, v252, 21
	s_mov_b64 s[0:1], -1
	s_and_b64 vcc, exec, s[8:9]
	s_cbranch_vccz .LBB0_906
	v_readlane_b32 s17, v250, 60
	v_readlane_b32 s6, v250, 57
	s_cmp_eq_u32 s17, 0
	s_cbranch_scc1 .Lg2g1_slow
	s_cmp_lg_u32 s6, 0
	s_cbranch_scc1 .Lg2g1_slow
	s_waitcnt vmcnt(0)
	s_barrier
	s_mov_b64 s[0:1], exec
	v_readlane_b32 s8, v252, 2
	v_readlane_b32 s9, v252, 3
	s_and_b64 s[8:9], s[0:1], s[8:9]
	s_mov_b64 exec, s[8:9]
	s_cbranch_execz .Lg2g1_join
	v_mov_b32_e32 v146, 0x23ff8
	ds_read_b32 v147, v146
	v_readlane_b32 s42, v250, 62
	v_mov_b32_e32 v146, 0
	s_mov_b32 s43, 0
	s_waitcnt lgkmcnt(0)
	v_readfirstlane_b32 s6, v147
	v_mov_b32_e32 v147, 1
	s_lshl_b32 s6, s6, 6
	s_add_i32 s6, s6, 0x7000
	s_add_u32 s40, s92, s6
	s_addc_u32 s41, s93, 0
	s_nop 4
	global_atomic_add v146, v147, s[40:41]

.Lg2g1_done:
	s_add_i32 s42, s42, 32
	s_nop 0
	v_writelane_b32 v250, s42, 62
	buffer_inv sc1

; DI void xcd_barrier(const XcdBarrier& b) {
;     asm volatile("s_waitcnt vmcnt(0)" ::: "memory");
;     __syncthreads();
;     if (threadIdx.x == 0) {
;         unsigned* bar = b.bar;
;         __builtin_amdgcn_s_waitcnt(0);
;         unsigned nloc = b.st[0], nx = b.st[1];
;         if (nloc == 0u) { xcd_barrier_complete(bar, b.x, nloc, nx); b.st[0] = nloc; b.st[1] = nx; }
.Lg2g1_slow:
	s_waitcnt vmcnt(0)
	s_waitcnt vmcnt(0)
	s_barrier
	s_mov_b64 s[0:1], exec
	v_readlane_b32 s8, v252, 2
	v_readlane_b32 s9, v252, 3
	s_and_b64 s[8:9], s[0:1], s[8:9]
	s_mov_b64 exec, s[8:9]
	s_cbranch_execz .LBB0_905
	v_readlane_b32 s6, v250, 9
	s_waitcnt vmcnt(0) expcnt(0) lgkmcnt(0)
	s_nop 0
	v_mov_b32_e32 v0, s6
	ds_read_b32 v3, v0
	v_readlane_b32 s6, v250, 10
	s_waitcnt lgkmcnt(0)
	v_cmp_ne_u32_e32 vcc, 0, v3
	v_mov_b32_e32 v0, s6
	ds_read_b32 v2, v0
	s_cbranch_vccnz .LBB0_869
	s_mov_b32 s6, 1
	s_branch .LBB0_857
